# grid barrier: non-leader workgroups poll the top-level generation word directly (one release hop instead of two)
# speedup vs baseline: 1.0019x; 1.0019x over previous
; __device__ __forceinline__ unsigned xb_ld(unsigned* p)              { return __hip_atomic_load(p, __ATOMIC_RELAXED, __HIP_MEMORY_SCOPE_AGENT); }
; __device__ __forceinline__ unsigned xb_add(unsigned* p, unsigned v) { return __hip_atomic_fetch_add(p, v, __ATOMIC_RELAXED, __HIP_MEMORY_SCOPE_AGENT); }
; #define XB_SPIN(cond, bar) do { unsigned _sp = 0; while (cond) { __builtin_amdgcn_s_sleep(1); \
;     if ((++_sp & 255u) == 0u) { if (xb_ld(&(bar)[XB_TMO])) break; if (_sp > XB_SPIN_CAP) { atomicAdd(&(bar)[XB_TMO], 1u); break; } } } } while (0)
; __device__ __forceinline__ void xcd_barrier(const XcdBarrier& b) {
;     ...
;         const unsigned old = xb_add(&bar[XB_XSUB(b.x)], 1u);
;         const unsigned gen = old / nloc;
;         if (old + 1u == (gen + 1u) * nloc) {
;             __builtin_amdgcn_fence(__ATOMIC_RELEASE, "agent");
;             asm volatile("s_waitcnt vmcnt(0)" ::: "memory");
;             const unsigned og = xb_add(&bar[XB_TOP], 1u);
;             const unsigned tg = og / nx;
;             if (og + 1u == (tg + 1u) * nx) xb_add(&bar[XB_TOPGEN], 1u);
;             else XB_SPIN(xb_ld(&bar[XB_TOPGEN]) == tg, bar);
;             __builtin_amdgcn_fence(__ATOMIC_ACQUIRE, "agent");
;             xb_add(&bar[XB_XGEN(b.x)], 1u);
;             asm volatile("s_waitcnt vmcnt(0)" ::: "memory");
;         } else {
;             XB_SPIN(xb_ld(&bar[XB_XGEN(b.x)]) == gen, bar);
;             __builtin_amdgcn_fence(__ATOMIC_ACQUIRE, "agent");
;             asm volatile("s_waitcnt vmcnt(0)" ::: "memory");
;         }
.LBB0_329:
	s_or_b64 exec, exec, s[10:11]
	v_cvt_f32_u32_e32 v5, v3
	s_waitcnt vmcnt(0)
	v_readfirstlane_b32 s3, v4
	v_sub_u32_e32 v4, 0, v3
	v_rcp_iflag_f32_e32 v5, v5
	v_add_u32_e32 v6, s3, v0
	v_mul_f32_e32 v5, 0x4f7ffffe, v5
	v_cvt_u32_f32_e32 v5, v5
	v_mul_lo_u32 v0, v4, v5
	v_mul_hi_u32 v0, v5, v0
	v_add_u32_e32 v0, v5, v0
	v_mul_hi_u32 v0, v6, v0
	v_mul_lo_u32 v4, v0, v3
	v_sub_u32_e32 v4, v6, v4
	v_add_u32_e32 v5, 1, v0
	v_cmp_ge_u32_e32 vcc, v4, v3
	s_nop 1
	v_cndmask_b32_e32 v0, v0, v5, vcc
	v_sub_u32_e32 v5, v4, v3
	v_cndmask_b32_e32 v4, v4, v5, vcc
	v_add_u32_e32 v5, 1, v0
	v_cmp_ge_u32_e32 vcc, v4, v3
	v_add_u32_e32 v4, 1, v6
	s_nop 0
	v_cndmask_b32_e32 v0, v0, v5, vcc
	v_mul_lo_u32 v5, v3, v0
	v_add_u32_e32 v3, v5, v3
	v_cmp_ne_u32_e32 vcc, v4, v3
	s_and_saveexec_b64 s[6:7], vcc
	s_xor_b64 s[10:11], exec, s[6:7]
	s_cbranch_execz .LBB0_343
	v_readlane_b32 s6, v250, 58
	v_readlane_b32 s7, v250, 59
	s_waitcnt lgkmcnt(0)
	s_nop 3
	global_load_dword v2, v1, s[6:7] sc1
	s_waitcnt vmcnt(0)
	v_cmp_eq_u32_e32 vcc, v2, v0
	s_and_saveexec_b64 s[18:19], vcc
	s_cbranch_execz .LBB0_342
	s_mov_b32 s3, 1
	s_mov_b64 s[38:39], 0
	s_branch .LBB0_333

; __device__ __forceinline__ unsigned xb_ld(unsigned* p)              { return __hip_atomic_load(p, __ATOMIC_RELAXED, __HIP_MEMORY_SCOPE_AGENT); }
; __device__ __forceinline__ unsigned xb_add(unsigned* p, unsigned v) { return __hip_atomic_fetch_add(p, v, __ATOMIC_RELAXED, __HIP_MEMORY_SCOPE_AGENT); }
; #define XB_SPIN(cond, bar) do { unsigned _sp = 0; while (cond) { __builtin_amdgcn_s_sleep(1); \
;     if ((++_sp & 255u) == 0u) { if (xb_ld(&(bar)[XB_TMO])) break; if (_sp > XB_SPIN_CAP) { atomicAdd(&(bar)[XB_TMO], 1u); break; } } } } while (0)
; __device__ __forceinline__ void xcd_barrier(const XcdBarrier& b) {
;     ...
;         const unsigned old = xb_add(&bar[XB_XSUB(b.x)], 1u);
;         const unsigned gen = old / nloc;
;         if (old + 1u == (gen + 1u) * nloc) {
;             __builtin_amdgcn_fence(__ATOMIC_RELEASE, "agent");
;             asm volatile("s_waitcnt vmcnt(0)" ::: "memory");
;             const unsigned og = xb_add(&bar[XB_TOP], 1u);
;             const unsigned tg = og / nx;
;             if (og + 1u == (tg + 1u) * nx) xb_add(&bar[XB_TOPGEN], 1u);
;             else XB_SPIN(xb_ld(&bar[XB_TOPGEN]) == tg, bar);
;             __builtin_amdgcn_fence(__ATOMIC_ACQUIRE, "agent");
;             xb_add(&bar[XB_XGEN(b.x)], 1u);
;             asm volatile("s_waitcnt vmcnt(0)" ::: "memory");
;         } else {
;             XB_SPIN(xb_ld(&bar[XB_XGEN(b.x)]) == gen, bar);
;             __builtin_amdgcn_fence(__ATOMIC_ACQUIRE, "agent");
;             asm volatile("s_waitcnt vmcnt(0)" ::: "memory");
;         }
.LBB0_676:
	s_or_b64 exec, exec, s[18:19]
	v_cvt_f32_u32_e32 v5, v3
	s_waitcnt vmcnt(0)
	v_readfirstlane_b32 s2, v4
	v_sub_u32_e32 v4, 0, v3
	v_rcp_iflag_f32_e32 v5, v5
	v_add_u32_e32 v6, s2, v0
	v_mul_f32_e32 v5, 0x4f7ffffe, v5
	v_cvt_u32_f32_e32 v5, v5
	v_mul_lo_u32 v0, v4, v5
	v_mul_hi_u32 v0, v5, v0
	v_add_u32_e32 v0, v5, v0
	v_mul_hi_u32 v0, v6, v0
	v_mul_lo_u32 v4, v0, v3
	v_sub_u32_e32 v4, v6, v4
	v_add_u32_e32 v5, 1, v0
	v_cmp_ge_u32_e32 vcc, v4, v3
	s_nop 1
	v_cndmask_b32_e32 v0, v0, v5, vcc
	v_sub_u32_e32 v5, v4, v3
	v_cndmask_b32_e32 v4, v4, v5, vcc
	v_add_u32_e32 v5, 1, v0
	v_cmp_ge_u32_e32 vcc, v4, v3
	v_add_u32_e32 v4, 1, v6
	s_nop 0
	v_cndmask_b32_e32 v0, v0, v5, vcc
	v_mul_lo_u32 v5, v3, v0
	v_add_u32_e32 v3, v5, v3
	v_cmp_ne_u32_e32 vcc, v4, v3
	s_and_saveexec_b64 s[2:3], vcc
	s_xor_b64 s[18:19], exec, s[2:3]
	s_cbranch_execz .LBB0_690
	v_readlane_b32 s2, v250, 58
	v_readlane_b32 s3, v250, 59
	s_waitcnt lgkmcnt(0)
	s_nop 3
	global_load_dword v2, v1, s[2:3] sc1
	s_waitcnt vmcnt(0)
	v_cmp_eq_u32_e32 vcc, v2, v0
	s_and_saveexec_b64 s[38:39], vcc
	s_cbranch_execz .LBB0_689
	s_mov_b32 s2, 1
	s_mov_b64 s[40:41], 0
	s_branch .LBB0_680

; __device__ __forceinline__ unsigned xb_ld(unsigned* p)              { return __hip_atomic_load(p, __ATOMIC_RELAXED, __HIP_MEMORY_SCOPE_AGENT); }
; __device__ __forceinline__ unsigned xb_add(unsigned* p, unsigned v) { return __hip_atomic_fetch_add(p, v, __ATOMIC_RELAXED, __HIP_MEMORY_SCOPE_AGENT); }
; #define XB_SPIN(cond, bar) do { unsigned _sp = 0; while (cond) { __builtin_amdgcn_s_sleep(1); \
;     if ((++_sp & 255u) == 0u) { if (xb_ld(&(bar)[XB_TMO])) break; if (_sp > XB_SPIN_CAP) { atomicAdd(&(bar)[XB_TMO], 1u); break; } } } } while (0)
; __device__ __forceinline__ void xcd_barrier(const XcdBarrier& b) {
;     ...
;         const unsigned old = xb_add(&bar[XB_XSUB(b.x)], 1u);
;         const unsigned gen = old / nloc;
;         if (old + 1u == (gen + 1u) * nloc) {
;             __builtin_amdgcn_fence(__ATOMIC_RELEASE, "agent");
;             asm volatile("s_waitcnt vmcnt(0)" ::: "memory");
;             const unsigned og = xb_add(&bar[XB_TOP], 1u);
;             const unsigned tg = og / nx;
;             if (og + 1u == (tg + 1u) * nx) xb_add(&bar[XB_TOPGEN], 1u);
;             else XB_SPIN(xb_ld(&bar[XB_TOPGEN]) == tg, bar);
;             __builtin_amdgcn_fence(__ATOMIC_ACQUIRE, "agent");
;             xb_add(&bar[XB_XGEN(b.x)], 1u);
;             asm volatile("s_waitcnt vmcnt(0)" ::: "memory");
;         } else {
;             XB_SPIN(xb_ld(&bar[XB_XGEN(b.x)]) == gen, bar);
;             __builtin_amdgcn_fence(__ATOMIC_ACQUIRE, "agent");
;             asm volatile("s_waitcnt vmcnt(0)" ::: "memory");
;         }
.LBB0_989:
	s_or_b64 exec, exec, s[8:9]
	v_cvt_f32_u32_e32 v5, v3
	s_waitcnt vmcnt(0)
	v_readfirstlane_b32 s2, v4
	v_sub_u32_e32 v4, 0, v3
	v_rcp_iflag_f32_e32 v5, v5
	v_add_u32_e32 v6, s2, v0
	v_mul_f32_e32 v5, 0x4f7ffffe, v5
	v_cvt_u32_f32_e32 v5, v5
	v_mul_lo_u32 v0, v4, v5
	v_mul_hi_u32 v0, v5, v0
	v_add_u32_e32 v0, v5, v0
	v_mul_hi_u32 v0, v6, v0
	v_mul_lo_u32 v4, v0, v3
	v_sub_u32_e32 v4, v6, v4
	v_add_u32_e32 v5, 1, v0
	v_cmp_ge_u32_e32 vcc, v4, v3
	s_nop 1
	v_cndmask_b32_e32 v0, v0, v5, vcc
	v_sub_u32_e32 v5, v4, v3
	v_cndmask_b32_e32 v4, v4, v5, vcc
	v_add_u32_e32 v5, 1, v0
	v_cmp_ge_u32_e32 vcc, v4, v3
	v_add_u32_e32 v4, 1, v6
	s_nop 0
	v_cndmask_b32_e32 v0, v0, v5, vcc
	v_mul_lo_u32 v5, v3, v0
	v_add_u32_e32 v3, v5, v3
	v_cmp_ne_u32_e32 vcc, v4, v3
	s_and_saveexec_b64 s[2:3], vcc
	s_xor_b64 s[8:9], exec, s[2:3]
	s_cbranch_execz .LBB0_1003
	v_readlane_b32 s2, v250, 58
	v_readlane_b32 s3, v250, 59
	s_waitcnt lgkmcnt(0)
	s_nop 3
	global_load_dword v2, v1, s[2:3] sc1
	s_waitcnt vmcnt(0)
	v_cmp_eq_u32_e32 vcc, v2, v0
	s_and_saveexec_b64 s[18:19], vcc
	s_cbranch_execz .LBB0_1002
	s_mov_b32 s2, 1
	s_mov_b64 s[38:39], 0
	s_branch .LBB0_993
